# MLA loop: K/V prefetch bases advanced in SGPRs, constant LDS addresses hoisted (7 fewer VALU per key tile)
# speedup vs baseline: 1.0028x; 1.0028x over previous
; DI int TID() { int t = (int)__builtin_amdgcn_workitem_id_x(); asm volatile("" : "+v"(t)); return t; }
; template <int DQK, int DV, bool BAND> ...
;     ...
;   const int tid = TID(), lane = tid & 63, w = tid >> 6, r32 = lane & 31, hi = lane >> 5;
;   u16* Ks = (u16*)smem; u16* Vs = (u16*)(smem + 17408); float* sc = (float*)(smem + 34816) + w * 64;
;   const int qw0 = q0 + w * 32, qi = qw0 + r32;
;   bf16x8 qf[ND0];
; #pragma unroll
;   for (int d0 = 0; d0 < ND0; ++d0) qf[d0] = *(const bf16x8*)(Q + (size_t)(w * 32 + r32) * ldq + d0 * 16 + hi * 8);
;   f32x16 o[NCB];
; #pragma unroll
;   for (int cb = 0; cb < NCB; ++cb)
; #pragma unroll
;     for (int r = 0; r < 16; ++r) o[cb][r] = 0.f;
;   float m_run = -INFINITY, l_run = 0.f;
;   int kt_lo = 0, kt_hi = nkeys >> 6;
;   if (BAND) { kt_lo = max(0, (q0 >> 6) - 1); kt_hi = min(nkeys >> 6, (q0 >> 6) + 3); }
;   u32x4 kreg[KCH], vreg[VCH];
;     ...
;   constexpr bool PREF = true;
;   if (PREF) ALOAD(kt_lo);
; DI void item_attn(const Params& p, int l, const Chunk& ck, int it, char* smem) {
;   const int S = ck.S;
;   if (it < 8 * MTN) {
;     static_assert(8 * MTN == 1024, "MLA item swizzle assumes 1024 items");
;     const int rnd = it >> 9, x = it & 7, jj = (it & 511) >> 3; const int qs = ck.sshift - 7, ppx = 64 >> qs;
;     const int bh = rnd * (8 * ppx) + x * ppx + (jj >> qs), qblk = jj & ((1 << qs) - 1);
;     const int h = bh & 7, bl = bh >> 3; const int t0 = qblk * 128, lt0 = bl * S + t0;
;     const u16* Q = (const u16*)(p.ws + OFF_QM) + (size_t)lt0 * 768 + h * 96;
;     const u16* K = (const u16*)(p.ws + OFF_KM) + (size_t)(bl * S) * 768 + h * 96;
;     const u16* Vt = (const u16*)(p.ws + OFF_VMT) + ((size_t)(bl * 8 + h) * 64) * S;
;     u16* O = (u16*)(p.ws + OFF_BR) + (size_t)(1 * CT + lt0) * 512 + h * 64;
;     (void)t0;
;     attn_block<96, 64, false>(Q, 768, K, 768, Vt, S, S, t0, 0.f, O, 512, nullptr, 0, smem);
.LBB1_317:
	s_ashr_i32 s21, s55, 6
	s_and_b32 s0, s55, 7
	s_and_b32 s29, s21, -8
	s_bfe_u32 s20, s55, 0x60003
	s_or_b32 s0, s29, s0
	s_lshr_b32 s30, s20, s35
	s_mul_i32 s0, s0, s42
	s_add_i32 s21, s0, s30
	s_and_b32 s20, s20, s43
	s_ashr_i32 s22, s21, 3
	s_lshl_b32 s20, s20, 7
	s_mul_i32 s26, s22, s2
	s_add_i32 s20, s26, s20
	s_and_b32 s28, s16, 7
	s_and_b32 s0, s21, 7
	s_mul_i32 s23, s20, 0x600
	s_mul_hi_i32 s22, s20, 0x600
	s_add_u32 s23, s93, s23
	s_addc_u32 s24, s94, s22
	s_mul_i32 s27, s0, 0xc0
	s_add_u32 s22, s23, s27
	v_mov_b32_e32 v2, v172
	s_addc_u32 s23, s24, 0
	s_mul_hi_i32 s25, s74, s21
	s_mul_i32 s24, s74, s21
	s_movk_i32 s21, 0xffe0
	v_ashrrev_i32_e32 v0, 1, v2
	v_bfe_u32 v3, v2, 5, 1
	s_waitcnt vmcnt(9)
	v_and_b32_e32 v122, 0xffffffe0, v0
	v_bfi_b32 v0, s21, v0, v2
	v_mov_b64_e32 v[4:5], s[22:23]
	s_movk_i32 s31, 0x600
	v_mad_i64_i32 v[4:5], s[22:23], v0, s31, v[4:5]
	v_lshlrev_b32_e32 v0, 4, v3
	v_lshl_add_u64 v[4:5], v[4:5], 0, v[0:1]
	global_load_dwordx4 v[66:69], v[4:5], off
	global_load_dwordx4 v[70:73], v[4:5], off offset:32
	global_load_dwordx4 v[74:77], v[4:5], off offset:64
	global_load_dwordx4 v[78:81], v[4:5], off offset:96
	global_load_dwordx4 v[82:85], v[4:5], off offset:128
	global_load_dwordx4 v[86:89], v[4:5], off offset:160
	v_lshlrev_b32_e32 v4, 2, v2
	s_mov_b32 s21, 0x2aaaaaab
	v_and_b32_e32 v29, 0xffffff00, v4
	v_mul_hi_i32 v4, v2, s21
	v_lshrrev_b32_e32 v5, 31, v4
	v_ashrrev_i32_e32 v4, 1, v4
	v_add_u32_e32 v30, v4, v5
	v_add_u32_e32 v4, 0x100, v2
	v_mul_hi_i32 v5, v4, s21
	v_lshrrev_b32_e32 v6, 31, v5
	v_ashrrev_i32_e32 v5, 1, v5
	v_add_u32_e32 v31, v5, v6
	v_add_u32_e32 v6, 0x200, v2
	s_lshl_b64 s[24:25], s[24:25], 1
	v_mul_hi_i32 v5, v6, s21
	v_ashrrev_i32_e32 v12, 3, v2
	s_waitcnt lgkmcnt(0)
	v_ashrrev_i32_e32 v16, 3, v4
	s_add_u32 s24, s17, s24
	v_lshrrev_b32_e32 v7, 31, v5
	v_ashrrev_i32_e32 v5, 1, v5
	v_mad_i64_i32 v[14:15], s[22:23], v12, s2, 0
	v_mad_i64_i32 v[18:19], s[22:23], v16, s2, 0
	s_addc_u32 s25, s34, s25
	v_add_u32_e32 v36, v5, v7
	v_lshlrev_b32_e32 v5, 4, v2
	s_mul_i32 s22, s26, 0x600
	v_and_b32_e32 v8, 0x70, v5
	v_mov_b32_e32 v9, v1
	s_mul_hi_i32 s23, s26, 0x600
	s_add_u32 s21, s79, s22
	v_lshl_add_u64 v[10:11], s[24:25], 0, v[8:9]
	s_addc_u32 s25, s92, s23
	s_add_u32 s24, s21, s27
	v_mad_u64_u32 v[6:7], s[26:27], v36, -12, v[6:7]
	s_addc_u32 s25, s25, 0
	v_lshlrev_b32_e32 v20, 3, v6
	v_mad_u64_u32 v[4:5], s[26:27], v31, -12, v[4:5]
	v_lshl_add_u64 v[18:19], v[18:19], 1, v[10:11]
	v_lshl_add_u64 v[10:11], v[14:15], 1, v[10:11]
	v_ashrrev_i32_e32 v21, 31, v20
	v_lshlrev_b32_e32 v22, 3, v4
	v_mad_u64_u32 v[24:25], s[26:27], v30, -12, v[2:3]
	global_load_dwordx4 v[94:97], v[18:19], off
	global_load_dwordx4 v[90:93], v[10:11], off
	v_mov_b64_e32 v[10:11], s[24:25]
	v_ashrrev_i32_e32 v23, 31, v22
	v_lshlrev_b32_e32 v26, 3, v24
	v_mad_i64_i32 v[14:15], s[24:25], v36, s31, v[10:11]
	v_lshlrev_b64 v[18:19], 1, v[20:21]
	v_ashrrev_i32_e32 v27, 31, v26
	v_lshl_add_u64 v[14:15], v[14:15], 0, v[18:19]
	v_mad_i64_i32 v[20:21], s[24:25], v31, s31, v[10:11]
	v_lshlrev_b64 v[22:23], 1, v[22:23]
	v_lshl_add_u64 v[20:21], v[20:21], 0, v[22:23]
	global_load_dwordx4 v[102:105], v[14:15], off
	global_load_dwordx4 v[98:101], v[20:21], off
	v_mad_i64_i32 v[10:11], s[24:25], v30, s31, v[10:11]
	v_lshlrev_b64 v[14:15], 1, v[26:27]
	v_lshl_add_u64 v[10:11], v[10:11], 0, v[14:15]
	global_load_dwordx4 v[106:109], v[10:11], off
	s_movk_i32 s24, 0xd0
	s_movk_i32 s26, 0x88
	v_mul_lo_u32 v38, v30, s24
	v_mul_lo_u32 v40, v31, s24
	v_mul_lo_u32 v42, v36, s24
	v_mad_u64_u32 v[32:33], s[24:25], v12, s26, v[8:9]
	v_mad_u64_u32 v[34:35], s[24:25], v16, s26, v[8:9]
	s_or_b32 s24, s29, s28
	s_mul_i32 s24, s42, s24
	s_add_i32 s24, s30, s24
	s_ashr_i32 s25, s24, 31
	v_and_b32_e32 v121, 31, v2
	v_ashrrev_i32_e32 v13, 31, v12
	v_or_b32_e32 v120, v29, v0
	s_lshl_b64 s[24:25], s[24:25], 7
	v_and_b32_e32 v0, 7, v2
	v_lshlrev_b32_e32 v28, 3, v3
	v_cmp_eq_u32_e64 s[36:37], 0, v3
	v_lshlrev_b32_e32 v123, 2, v3
	v_mul_u32_u24_e32 v3, 0x44, v121
	v_lshlrev_b32_e32 v39, 4, v4
	v_lshl_add_u64 v[4:5], v[12:13], 1, s[24:25]
	v_lshlrev_b32_e32 v0, 4, v0
	v_lshl_add_u32 v125, v3, 1, v28
	v_mad_u64_u32 v[2:3], s[26:27], s2, v4, v[0:1]
	v_ashrrev_i32_e32 v17, 31, v16
	v_mad_i32_i24 v3, s2, v5, v3
	s_mov_b64 s[26:27], 0x15080080
	v_lshl_add_u64 v[110:111], v[2:3], 0, s[26:27]
	v_lshl_add_u64 v[2:3], v[16:17], 1, s[24:25]
	v_mad_u64_u32 v[4:5], s[24:25], s2, v2, v[0:1]
	v_mad_i32_i24 v5, s2, v3, v5
	v_mov_b64_e32 v[2:3], s[22:23]
	v_lshl_add_u64 v[112:113], v[4:5], 0, s[26:27]
	v_mad_i64_i32 v[4:5], s[22:23], v36, s31, v[2:3]
	s_mov_b64 s[26:27], 0x13898000
	s_add_i32 s22, s54, s30
	v_lshl_add_u64 v[4:5], v[4:5], 0, s[26:27]
	s_and_b32 s24, s22, 7
	v_mad_u64_u32 v[4:5], s[22:23], s24, v203, v[4:5]
	s_waitcnt vmcnt(19)
	v_lshl_add_u64 v[114:115], v[4:5], 0, v[18:19]
	v_mad_i64_i32 v[4:5], s[22:23], v31, s31, v[2:3]
	v_mad_i64_i32 v[2:3], s[22:23], v30, s31, v[2:3]
	v_lshl_add_u64 v[4:5], v[4:5], 0, s[26:27]
	v_lshl_add_u64 v[2:3], v[2:3], 0, s[26:27]
	v_mad_u64_u32 v[4:5], s[22:23], s24, v203, v[4:5]
	v_mad_u64_u32 v[2:3], s[22:23], s24, v203, v[2:3]
	v_lshl_or_b32 v124, v121, 2, v29
	v_lshlrev_b32_e32 v37, 4, v24
	v_lshlrev_b32_e32 v41, 4, v6
	v_add_u32_e32 v33, v28, v28
	v_mul_u32_u24_e32 v35, 0xd0, v121
	v_lshl_add_u64 v[116:117], v[4:5], 0, v[22:23]
	v_lshl_add_u64 v[118:119], v[2:3], 0, v[14:15]
	v_mov_b32_e32 v2, v1
	v_mov_b32_e32 v3, v1
	v_mov_b32_e32 v4, v1
	v_mov_b32_e32 v5, v1
	v_mov_b32_e32 v6, v1
	v_mov_b32_e32 v7, v1
	v_mov_b32_e32 v8, v1
	v_mov_b32_e32 v10, v1
	v_mov_b32_e32 v11, v1
	v_mov_b32_e32 v12, v1
	v_mov_b32_e32 v13, v1
	v_mov_b32_e32 v14, v1
	v_mov_b32_e32 v15, v1
	v_mov_b32_e32 v16, v1
	v_mov_b32_e32 v17, v1
	v_mov_b32_e32 v18, v1
	v_mov_b32_e32 v19, v1
	v_mov_b32_e32 v20, v1
	v_mov_b32_e32 v21, v1
	v_mov_b32_e32 v22, v1
	v_mov_b32_e32 v23, v1
	v_mov_b32_e32 v24, v1
	v_mov_b32_e32 v25, v1
	v_mov_b32_e32 v26, v1
	v_mov_b32_e32 v27, v1
	v_mov_b32_e32 v28, v1
	v_mov_b32_e32 v29, v1
	v_mov_b32_e32 v30, v1
	v_mov_b32_e32 v31, v1
	v_mov_b32_e32 v0, v1
	v_add_u32_e32 v130, 0x4400, v32
	v_add_u32_e32 v132, v33, v35
	v_mov_b64_e32 v[32:33], v[30:31]
	s_mov_b32 s21, 0
	s_waitcnt vmcnt(18)
; template <int DQK, int DV, bool BAND> ...
;     ...
;     for (int r = 0; r < 16; ++r) o[cb][r] = 0.f;
;   float m_run = -INFINITY, l_run = 0.f;
;   int kt_lo = 0, kt_hi = nkeys >> 6;
;   if (BAND) { kt_lo = max(0, (q0 >> 6) - 1); kt_hi = min(nkeys >> 6, (q0 >> 6) + 3); }
;   u32x4 kreg[KCH], vreg[VCH];
;     ...
;   constexpr bool PREF = true;
;   if (PREF) ALOAD(kt_lo);
;   for (int kt = kt_lo; kt < kt_hi; ++kt) {
;     __syncthreads();
;     if (!PREF) ALOAD(kt);
; #pragma unroll
;     for (int i = 0; i < KCH; ++i) { const int cid = tid + 256 * i, row = cid / KCPR, c8 = cid - row * KCPR; *(u32x4*)&Ks[row * KLD + c8 * 8] = kreg[i]; }
; #pragma unroll
;     for (int i = 0; i < VCH; ++i) { const int cid = tid + 256 * i, row = cid >> 3, c8 = cid & 7;
;       *(u32x2*)&Vs[row * VLD + c8 * 8] = u32x2{vreg[i][0], vreg[i][1]}; *(u32x2*)&Vs[row * VLD + c8 * 8 + 4] = u32x2{vreg[i][2], vreg[i][3]}; }
;     __syncthreads();
;     if (PREF && kt + 1 < kt_hi) ALOAD(kt + 1);
	v_mov_b32_e32 v126, 0
	v_mov_b32_e32 v133, 0xff800000
	v_add_u32_e32 v127, v37, v38
	v_add_u32_e32 v128, v39, v40
	v_add_u32_e32 v129, v41, v42
	v_add_u32_e32 v131, 0x4400, v34
	v_mov_b64_e32 v[30:31], v[28:29]
	v_mov_b64_e32 v[28:29], v[26:27]
	v_mov_b64_e32 v[26:27], v[24:25]
	v_mov_b64_e32 v[24:25], v[22:23]
	v_mov_b64_e32 v[22:23], v[20:21]
	v_mov_b64_e32 v[20:21], v[18:19]
	v_mov_b64_e32 v[18:19], v[16:17]
	v_mov_b64_e32 v[16:17], v[14:15]
	v_mov_b64_e32 v[14:15], v[12:13]
	v_mov_b64_e32 v[12:13], v[10:11]
	v_mov_b64_e32 v[10:11], v[8:9]
	v_mov_b64_e32 v[8:9], v[6:7]
	v_mov_b64_e32 v[6:7], v[4:5]
	v_mov_b64_e32 v[4:5], v[2:3]
	v_mov_b64_e32 v[2:3], v[0:1]
	v_mov_b32_e32 v150, 0
	v_mov_b32_e32 v151, 0
	v_mov_b32_e32 v152, 0
	v_mov_b32_e32 v153, 0
	v_mov_b32_e32 v154, 0
	v_mov_b32_e32 v155, 0
	v_mov_b32_e32 v156, 0
	v_mov_b32_e32 v157, 0
	v_mov_b32_e32 v158, 0
	v_mov_b32_e32 v159, 0
	v_mov_b32_e32 v160, 0
	v_mov_b32_e32 v161, 0
	v_mov_b32_e32 v162, 0
	v_mov_b32_e32 v163, 0
	v_mov_b32_e32 v164, 0
	v_mov_b32_e32 v165, 0
	v_add_u32_e32 v166, 0x4000, v125
	v_add_u32_e32 v167, 0x5000, v125
	s_mov_b64 s[12:13], s[18:19]
	s_mov_b64 s[14:15], s[18:19]
.LBB1_318:
	s_add_i32 s21, s21, 1
	s_cmp_ge_u32 s21, s75
	s_barrier
	s_waitcnt vmcnt(0)
	ds_write_b128 v127, v[106:109]
	ds_write_b128 v128, v[98:101]
	ds_write_b128 v129, v[102:105]
	ds_write2_b64 v130, v[90:91], v[92:93] offset1:1
	ds_write2_b64 v131, v[94:95], v[96:97] offset1:1
	s_waitcnt lgkmcnt(0)
	s_barrier
	s_cbranch_scc1 .LBB1_320
	global_load_dwordx4 v[106:109], v118, s[14:15]
	global_load_dwordx4 v[98:101], v116, s[14:15]
	global_load_dwordx4 v[102:105], v114, s[14:15]
	global_load_dwordx4 v[90:93], v110, s[12:13]
	global_load_dwordx4 v[94:97], v112, s[12:13]
; #define MFMA(a, b, c) __builtin_amdgcn_mfma_f32_32x32x16_bf16((a), (b), (c), 0, 0, 0)
; DI float xhalf_max(float x) { const auto rr = __builtin_amdgcn_permlane32_swap(__float_as_uint(x), __float_as_uint(x), false, false); return fmaxf(__uint_as_float(rr[0]), __uint_as_float(rr[1])); }
; template <int DQK, int DV, bool BAND> ...
;     ...
;     if constexpr (DQK < 128) {
;       f32x16 p0, p1;
; #pragma unroll
;       for (int r = 0; r < 16; ++r) { p0[r] = 0.f; p1[r] = 0.f; }
;       __builtin_amdgcn_s_setprio(1);
; #pragma unroll
;       for (int d0 = 0; d0 < ND0; ++d0) {
;         const bf16x8 k0f = *(const bf16x8*)&Ks[r32 * KLD + d0 * 16 + hi * 8];
;         const bf16x8 k1f = *(const bf16x8*)&Ks[(32 + r32) * KLD + d0 * 16 + hi * 8];
;         p0 = MFMA(k0f, qf[d0], p0); p1 = MFMA(k1f, qf[d0], p1);
;       }
;       __builtin_amdgcn_s_setprio(0);
;       float mx = fmaxf(p0[0], p1[0]);
; #pragma unroll
;       for (int r = 1; r < 16; ++r) mx = fmaxf(mx, fmaxf(p0[r], p1[r]));
;       mx = xhalf_max(mx);
;       if (__builtin_amdgcn_ballot_w64(mx > m_run + 8.f) != 0ull) {
;         const float m_new = fmaxf(m_run, mx); const float m_use = (m_new == -INFINITY) ? 0.f : m_new;
;         const float alpha = __builtin_amdgcn_exp2f(m_run - m_use);
;         l_run *= alpha; m_run = m_new;
;         if (hi == 0) sc[r32] = alpha;
;         __builtin_amdgcn_fence(__ATOMIC_RELEASE, "wavefront");
;         __builtin_amdgcn_wave_barrier();
; #pragma unroll
;         for (int g4 = 0; g4 < 4; ++g4) { const f32x4 a4 = *(const f32x4*)&sc[8 * g4 + 4 * hi];
; #pragma unroll
;           for (int cb = 0; cb < NCB; ++cb)
; #pragma unroll
;             for (int j = 0; j < 4; ++j) o[cb][4 * g4 + j] *= a4[j]; }
;         __builtin_amdgcn_wave_barrier();
;       }
;       const float m_ref = (m_run == -INFINITY) ? 0.f : m_run;
.LBB1_320:
	s_setprio 1
	ds_read_b128 v[208:211], v132
	ds_read_b128 v[212:215], v132 offset:6656
	ds_read_b128 v[216:219], v132 offset:32
	ds_read_b128 v[220:223], v132 offset:6688
	ds_read_b128 v[224:227], v132 offset:64
	ds_read_b128 v[228:231], v132 offset:6720
	ds_read_b128 v[232:235], v132 offset:96
	ds_read_b128 v[236:239], v132 offset:6752
	ds_read_b128 v[240:243], v132 offset:128
	ds_read_b128 v[244:247], v132 offset:6784
	ds_read_b128 v[248:251], v132 offset:160
	ds_read_b128 v[134:137], v132 offset:6816
	s_waitcnt lgkmcnt(11)
	v_mfma_f32_32x32x16_bf16 v[34:49], v[208:211], v[66:69], v[150:165]
	s_waitcnt lgkmcnt(10)
	v_mfma_f32_32x32x16_bf16 v[50:65], v[212:215], v[66:69], v[150:165]
	s_waitcnt lgkmcnt(9)
	v_mfma_f32_32x32x16_bf16 v[34:49], v[216:219], v[70:73], v[34:49]
	s_waitcnt lgkmcnt(8)
	v_mfma_f32_32x32x16_bf16 v[50:65], v[220:223], v[70:73], v[50:65]
	s_waitcnt lgkmcnt(7)
	v_mfma_f32_32x32x16_bf16 v[34:49], v[224:227], v[74:77], v[34:49]
	s_waitcnt lgkmcnt(6)
	v_mfma_f32_32x32x16_bf16 v[50:65], v[228:231], v[74:77], v[50:65]
	s_waitcnt lgkmcnt(5)
	v_mfma_f32_32x32x16_bf16 v[34:49], v[232:235], v[78:81], v[34:49]
	s_waitcnt lgkmcnt(4)
	v_mfma_f32_32x32x16_bf16 v[50:65], v[236:239], v[78:81], v[50:65]
	s_waitcnt lgkmcnt(3)
	v_mfma_f32_32x32x16_bf16 v[34:49], v[240:243], v[82:85], v[34:49]
	s_waitcnt lgkmcnt(2)
	v_mfma_f32_32x32x16_bf16 v[50:65], v[244:247], v[82:85], v[50:65]
	s_waitcnt lgkmcnt(1)
	v_mfma_f32_32x32x16_bf16 v[34:49], v[248:251], v[86:89], v[34:49]
	s_waitcnt lgkmcnt(0)
	v_mfma_f32_32x32x16_bf16 v[50:65], v[134:137], v[86:89], v[50:65]
	s_setprio 0
	ds_read2_b64 v[208:211], v166 offset0:128 offset1:130
	ds_read2_b64 v[212:215], v167 offset0:160 offset1:162
	ds_read2_b64 v[216:219], v166 offset0:136 offset1:138
	ds_read2_b64 v[220:223], v167 offset0:168 offset1:170
	ds_read2_b64 v[224:227], v166 offset0:132 offset1:134
	ds_read2_b64 v[228:231], v167 offset0:164 offset1:166
	ds_read2_b64 v[232:235], v166 offset0:140 offset1:142
	ds_read2_b64 v[236:239], v167 offset0:172 offset1:174
	s_nop 10
	v_max3_f32 v0, v34, v50, v35
	v_max3_f32 v134, v51, v36, v52
	v_max3_f32 v0, v0, v37, v53
	v_max3_f32 v134, v134, v38, v54
	v_max3_f32 v0, v0, v39, v55
	v_max3_f32 v134, v134, v40, v56
	v_max3_f32 v0, v0, v41, v57
	v_max3_f32 v134, v134, v42, v58
	v_max3_f32 v0, v0, v43, v59
	v_max3_f32 v134, v134, v44, v60
	v_max3_f32 v0, v0, v45, v61
	v_max3_f32 v134, v134, v46, v62
	v_max3_f32 v0, v0, v47, v63
	v_max3_f32 v134, v134, v48, v64
	v_max3_f32 v0, v0, v49, v65
	v_max_f32_e32 v0, v0, v134
	v_mov_b32_e32 v134, v0
	s_nop 1
	v_permlane32_swap_b32_e32 v0, v134
	v_max_f32_e32 v0, v0, v134
	v_sub_f32_e32 v0, v0, v150
	v_add_f32_e32 v134, 0x41000000, v133
	v_cmp_gt_f32_e32 vcc, v0, v134
	s_cbranch_vccz .LBB1_324
	v_max_f32_e32 v0, v0, v0
	v_max_f32_e32 v134, v133, v133
	v_max_f32_e32 v0, v134, v0
	v_cmp_neq_f32_e32 vcc, s7, v0
	s_nop 1
	v_cndmask_b32_e32 v134, 0, v0, vcc
	v_sub_f32_e32 v133, v133, v134
	v_exp_f32_e32 v133, v133
	v_add_f32_e32 v168, v150, v134
	s_and_saveexec_b64 s[22:23], s[36:37]
	ds_write_b32 v124, v133 offset:34816
	s_or_b64 exec, exec, s[22:23]
	s_waitcnt lgkmcnt(0)
	ds_read_b128 v[136:139], v120 offset:34816
	ds_read_b128 v[140:143], v120 offset:34848
	ds_read_b128 v[144:147], v120 offset:34880
	ds_read_b128 v[240:243], v120 offset:34912
	v_mul_f32_e32 v126, v126, v133
	v_sub_f32_e32 v34, v34, v168
	v_sub_f32_e32 v35, v35, v168
	v_sub_f32_e32 v36, v36, v168
	v_sub_f32_e32 v37, v37, v168
	v_sub_f32_e32 v38, v38, v168
	v_sub_f32_e32 v39, v39, v168
	v_sub_f32_e32 v40, v40, v168
	v_sub_f32_e32 v41, v41, v168
	v_sub_f32_e32 v42, v42, v168
	v_sub_f32_e32 v43, v43, v168
	v_sub_f32_e32 v44, v44, v168
	v_sub_f32_e32 v45, v45, v168
	v_sub_f32_e32 v46, v46, v168
	v_sub_f32_e32 v47, v47, v168
	v_sub_f32_e32 v48, v48, v168
	v_sub_f32_e32 v49, v49, v168
	v_sub_f32_e32 v50, v50, v168
	v_sub_f32_e32 v51, v51, v168
	v_sub_f32_e32 v52, v52, v168
	v_sub_f32_e32 v53, v53, v168
	v_sub_f32_e32 v54, v54, v168
	v_sub_f32_e32 v55, v55, v168
	v_sub_f32_e32 v56, v56, v168
	v_sub_f32_e32 v57, v57, v168
	v_sub_f32_e32 v58, v58, v168
	v_sub_f32_e32 v59, v59, v168
	v_sub_f32_e32 v60, v60, v168
	v_sub_f32_e32 v61, v61, v168
	v_sub_f32_e32 v62, v62, v168
	v_sub_f32_e32 v63, v63, v168
	v_sub_f32_e32 v64, v64, v168
	v_sub_f32_e32 v65, v65, v168
	v_sub_f32_e32 v150, 0, v134
	v_mov_b32_e32 v151, v150
	v_mov_b32_e32 v152, v150
	v_mov_b32_e32 v153, v150
	v_mov_b32_e32 v154, v150
	v_mov_b32_e32 v155, v150
	v_mov_b32_e32 v156, v150
	v_mov_b32_e32 v157, v150
	v_mov_b32_e32 v158, v150
	v_mov_b32_e32 v159, v150
	v_mov_b32_e32 v160, v150
	v_mov_b32_e32 v161, v150
	v_mov_b32_e32 v162, v150
	v_mov_b32_e32 v163, v150
	v_mov_b32_e32 v164, v150
	v_mov_b32_e32 v165, v150
	s_waitcnt lgkmcnt(0)
	v_pk_mul_f32 v[2:3], v[2:3], v[136:137]
	v_pk_mul_f32 v[4:5], v[4:5], v[138:139]
	v_pk_mul_f32 v[6:7], v[6:7], v[140:141]
	v_pk_mul_f32 v[8:9], v[8:9], v[142:143]
	v_pk_mul_f32 v[10:11], v[10:11], v[144:145]
	v_pk_mul_f32 v[12:13], v[12:13], v[146:147]
	v_pk_mul_f32 v[14:15], v[14:15], v[240:241]
	v_pk_mul_f32 v[16:17], v[16:17], v[242:243]
	v_pk_mul_f32 v[18:19], v[18:19], v[136:137]
	v_pk_mul_f32 v[20:21], v[20:21], v[138:139]
	v_pk_mul_f32 v[22:23], v[22:23], v[140:141]
	v_pk_mul_f32 v[24:25], v[24:25], v[142:143]
	v_pk_mul_f32 v[26:27], v[26:27], v[144:145]
	v_pk_mul_f32 v[28:29], v[28:29], v[146:147]
	v_pk_mul_f32 v[30:31], v[30:31], v[240:241]
	v_pk_mul_f32 v[32:33], v[32:33], v[242:243]
	s_branch .LBB1_325

; #define MFMA(a, b, c) __builtin_amdgcn_mfma_f32_32x32x16_bf16((a), (b), (c), 0, 0, 0)
; DI unsigned pk2(float a, float b) { f2_t v = {a, b}; bf2_t r = __builtin_convertvector(v, bf2_t); return __builtin_bit_cast(unsigned, r); }
; DI float xhalf_sum(float x) { const auto rr = __builtin_amdgcn_permlane32_swap(__float_as_uint(x), __float_as_uint(x), false, false); return __uint_as_float(rr[0]) + __uint_as_float(rr[1]); }
; template <int DQK, int DV, bool BAND> ...
;     ...
;     if (PREF && kt + 1 < kt_hi) ALOAD(kt + 1);
;     ...
;       const float m_ref = (m_run == -INFINITY) ? 0.f : m_run;
;       float rs0 = 0.f, rs1 = 0.f;
; #pragma unroll
;       for (int r = 0; r < 16; ++r) { const float e0 = __builtin_amdgcn_exp2f(p0[r] - m_ref), e1 = __builtin_amdgcn_exp2f(p1[r] - m_ref); p0[r] = e0; p1[r] = e1; rs0 += e0; rs1 += e1; }
;       l_run += xhalf_sum(rs0 + rs1);
;       __builtin_amdgcn_s_setprio(1);
; #pragma unroll
;       for (int s = 0; s < 2; ++s) {
;         const u32x4 pu0 = {pk2(p0[8 * s], p0[8 * s + 1]), pk2(p0[8 * s + 2], p0[8 * s + 3]), pk2(p0[8 * s + 4], p0[8 * s + 5]), pk2(p0[8 * s + 6], p0[8 * s + 7])};
;         const u32x4 pu1 = {pk2(p1[8 * s], p1[8 * s + 1]), pk2(p1[8 * s + 2], p1[8 * s + 3]), pk2(p1[8 * s + 4], p1[8 * s + 5]), pk2(p1[8 * s + 6], p1[8 * s + 7])};
; #pragma unroll
;         for (int cb = 0; cb < NCB; ++cb) {
;           const u32x2 lo0 = *(const u32x2*)&Vs[(cb * 32 + r32) * VLD + 16 * s + 4 * hi];
;           const u32x2 hi0 = *(const u32x2*)&Vs[(cb * 32 + r32) * VLD + 16 * s + 4 * hi + 8];
;           const u32x4 v0 = {lo0[0], lo0[1], hi0[0], hi0[1]};
;           o[cb] = MFMA(__builtin_bit_cast(bf16x8, pu0), __builtin_bit_cast(bf16x8, v0), o[cb]);
;         }
; #pragma unroll
;         for (int cb = 0; cb < NCB; ++cb) {
;           const u32x2 lo1 = *(const u32x2*)&Vs[(cb * 32 + r32) * VLD + 32 + 16 * s + 4 * hi];
;           const u32x2 hi1 = *(const u32x2*)&Vs[(cb * 32 + r32) * VLD + 32 + 16 * s + 4 * hi + 8];
;           const u32x4 v1 = {lo1[0], lo1[1], hi1[0], hi1[1]};
;           o[cb] = MFMA(__builtin_bit_cast(bf16x8, pu1), __builtin_bit_cast(bf16x8, v1), o[cb]);
;         }
;       }
;       __builtin_amdgcn_s_setprio(0);
.LBB1_325:
	v_exp_f32_e32 v34, v34
	v_exp_f32_e32 v35, v35
	v_exp_f32_e32 v36, v36
	v_exp_f32_e32 v37, v37
	v_exp_f32_e32 v38, v38
	v_exp_f32_e32 v39, v39
	v_exp_f32_e32 v40, v40
	v_exp_f32_e32 v41, v41
	v_exp_f32_e32 v42, v42
	v_exp_f32_e32 v43, v43
	v_exp_f32_e32 v44, v44
	v_exp_f32_e32 v45, v45
	v_exp_f32_e32 v46, v46
	v_exp_f32_e32 v47, v47
	v_exp_f32_e32 v48, v48
	v_exp_f32_e32 v49, v49
	v_exp_f32_e32 v50, v50
	v_exp_f32_e32 v51, v51
	v_exp_f32_e32 v52, v52
	v_exp_f32_e32 v53, v53
	v_exp_f32_e32 v54, v54
	v_exp_f32_e32 v55, v55
	v_exp_f32_e32 v56, v56
	v_exp_f32_e32 v57, v57
	v_exp_f32_e32 v58, v58
	v_exp_f32_e32 v59, v59
	v_exp_f32_e32 v60, v60
	v_exp_f32_e32 v61, v61
	v_exp_f32_e32 v62, v62
	v_exp_f32_e32 v63, v63
	v_exp_f32_e32 v64, v64
	v_exp_f32_e32 v65, v65
	s_nop 0
	v_pk_add_f32 v[168:169], v[34:35], v[36:37]
	v_pk_add_f32 v[170:171], v[38:39], v[40:41]
	v_pk_add_f32 v[168:169], v[42:43], v[168:169]
	v_pk_add_f32 v[170:171], v[44:45], v[170:171]
	v_pk_add_f32 v[168:169], v[46:47], v[168:169]
	v_pk_add_f32 v[170:171], v[48:49], v[170:171]
	v_pk_add_f32 v[168:169], v[50:51], v[168:169]
	v_pk_add_f32 v[170:171], v[52:53], v[170:171]
	v_pk_add_f32 v[168:169], v[54:55], v[168:169]
	v_pk_add_f32 v[170:171], v[56:57], v[170:171]
	v_pk_add_f32 v[168:169], v[58:59], v[168:169]
	v_pk_add_f32 v[170:171], v[60:61], v[170:171]
	v_pk_add_f32 v[168:169], v[62:63], v[168:169]
	v_pk_add_f32 v[170:171], v[64:65], v[170:171]
	v_pk_add_f32 v[168:169], v[168:169], v[170:171]
	s_nop 0
	v_add_f32_e32 v168, v168, v169
	v_mov_b32_e32 v169, v168
	s_nop 1
	v_permlane32_swap_b32_e32 v168, v169
	v_add_f32_e32 v168, v168, v169
	v_add_f32_e32 v126, v126, v168
	v_cvt_pk_bf16_f32 v34, v34, v35
	v_cvt_pk_bf16_f32 v35, v36, v37
	v_cvt_pk_bf16_f32 v36, v38, v39
	v_cvt_pk_bf16_f32 v37, v40, v41
	v_cvt_pk_bf16_f32 v38, v42, v43
	v_cvt_pk_bf16_f32 v39, v44, v45
	v_cvt_pk_bf16_f32 v40, v46, v47
	v_cvt_pk_bf16_f32 v41, v48, v49
	v_cvt_pk_bf16_f32 v50, v50, v51
	v_cvt_pk_bf16_f32 v51, v52, v53
	v_cvt_pk_bf16_f32 v52, v54, v55
	v_cvt_pk_bf16_f32 v53, v56, v57
	v_cvt_pk_bf16_f32 v54, v58, v59
	v_cvt_pk_bf16_f32 v55, v60, v61
	v_cvt_pk_bf16_f32 v56, v62, v63
	v_cvt_pk_bf16_f32 v57, v64, v65
	s_setprio 1
	s_waitcnt lgkmcnt(0)
	v_mfma_f32_32x32x16_bf16 v[2:17], v[34:37], v[208:211], v[2:17]
	v_mfma_f32_32x32x16_bf16 v[18:33], v[34:37], v[212:215], v[18:33]
	v_mfma_f32_32x32x16_bf16 v[2:17], v[50:53], v[216:219], v[2:17]
	v_mfma_f32_32x32x16_bf16 v[18:33], v[50:53], v[220:223], v[18:33]
	v_mfma_f32_32x32x16_bf16 v[2:17], v[38:41], v[224:227], v[2:17]
	v_mfma_f32_32x32x16_bf16 v[18:33], v[38:41], v[228:231], v[18:33]
	v_mfma_f32_32x32x16_bf16 v[2:17], v[54:57], v[232:235], v[2:17]
	v_mfma_f32_32x32x16_bf16 v[18:33], v[54:57], v[236:239], v[18:33]
	s_setprio 0
	s_add_u32 s12, s12, s8
	s_addc_u32 s13, s13, s9
	s_add_u32 s14, s14, s10
	s_addc_u32 s15, s15, s11
	s_cmp_eq_u32 s75, s21
	s_cbranch_scc1 .LBB1_327
	v_mov_b32_e32 v133, v0
	s_branch .LBB1_318
